# v62 variant: ai=1 half of the split epilogue moved entirely to the next unit's second load segment (first segment keeps only the unit-head code)
# baseline (speedup 1.0000x reference)
; __device__ __forceinline__ unsigned cvt_pk_bf16(float lo, float hi) { const f32x2_t v = {lo, hi}; const bf16x2_t c = __builtin_convertvector(v, bf16x2_t); return __builtin_bit_cast(unsigned, c); }
; #define PG8_STAGE(bufoff, gbase, voff) do { _Pragma("unroll") for (int _i = 0; _i < 2; ++_i) \
;         __builtin_amdgcn_global_load_lds((const unsigned*)((const char*)(gbase) + (voff)[_i]), (PG8_LAS unsigned*)(lds + (bufoff) + ldsw + _i * 8192), 16, 0, 0); } while (0)
; #define PG8_LDA(dst, b, h) do { _Pragma("unroll") for (int m = 0; m < 4; ++m) _Pragma("unroll") for (int k = 0; k < 2; ++k) dst[m][k] = *(const PG8_LAS bf16x8*)(lds + PG8_SA(b, h) + aoff + m * 2048 + k * 1024); } while (0)
; #define PG8_LDB(dst, b, h) do { _Pragma("unroll") for (int n = 0; n < 2; ++n) _Pragma("unroll") for (int k = 0; k < 2; ++k) dst[n][k] = *(const PG8_LAS bf16x8*)(lds + PG8_SB(b, h) + boff + n * 2048 + k * 1024); } while (0)
; #define PG8_WAIT_V(n) asm volatile("s_waitcnt vmcnt(" #n ")" ::: "memory")
; #define PG8_BAR __builtin_amdgcn_s_barrier()
;     __device__ __forceinline__ void operator()(const f32x4 (&acc)[2][2][4][2], const Unit& u, int wr, int wc, int fr, int fq) const {
;     ...
;             for (int m = 0; m < 4; ++m) { bf16_t* rowp = O + (size_t)(row0 + ai * HALF + m * 16) * ldc + col0;
; #pragma unroll
;                 for (int bj = 0; bj < 2; ++bj) { const f32x4 v0 = acc[ai][bj][m][0], v1 = acc[ai][bj][m][1];
;                     u32x4 w; w.x = cvt_pk_bf16(v0[0], v0[1]); w.y = cvt_pk_bf16(v0[2], v0[3]); w.z = cvt_pk_bf16(v1[0], v1[1]); w.w = cvt_pk_bf16(v1[2], v1[3]);
;                     *(u32x4*)(rowp + bj * HALF) = w; } }
; template <class Epi, class Sched, bool ALIGN_EPI = false, bool SP2 = false, bool KHOOK = false>
; __device__ __forceinline__ void gemm_phase(PG8_LAS unsigned char* lds, const Gemm g, const Sched& S, const Epi& E, const int tid_in) {
;     ...
;             PG8_LDB(B0, 0, 0); PG8_LDB(B1, 0, 1); PG8_SCHED; PG8_LDA(At, 0, 0); PG8_STAGE(PG8_SA(1, 1), a1 + hstep, voffA);
;             PG8_WAIT_V(8); PG8_WAIT_L(0); PG8_BAR; PG8_MMA(0, 0, At, B0); PG8_MMA(0, 1, At, B1); PG8_BAR; PG8_SCHED;
;             PG8_LDA(At, 0, 1); PG8_STAGE(PG8_SB(0, 0), b2, voffB); PG8_STAGE(PG8_SB(0, 1), b2 + hstep, voffB); PG8_STAGE(PG8_SA(0, 0), a2, voffA);
;             PG8_WAIT_V(8); PG8_WAIT_L(0); PG8_BAR; PG8_MMA(1, 0, At, B0); PG8_MMA(1, 1, At, B1); PG8_BAR; PG8_SCHED;
.Lg1_peel_e1:
	s_add_u32 s45, s48, 0xfff80080
	s_addc_u32 s46, s49, -1
	s_add_i32 s47, 0, 0x10000
	s_cmp_eq_u32 s44, 28
	s_cselect_b32 s57, s11, s46
	s_cselect_b32 s56, s17, s45
	s_cselect_b32 s53, s15, s42
	s_cselect_b32 s52, s18, s19
	s_add_i32 s45, 0, 0x14000
	v_add_u32_e32 v156, s47, v141
	v_add_u32_e32 v172, s45, v141
	ds_read_b128 v[144:147], v156
	ds_read_b128 v[148:151], v156 offset:1024
	ds_read_b128 v[152:155], v156 offset:2048
	ds_read_b128 v[156:159], v156 offset:3072
	ds_read_b128 v[160:163], v172
	ds_read_b128 v[164:167], v172 offset:1024
	ds_read_b128 v[168:171], v172 offset:2048
	ds_read_b128 v[172:175], v172 offset:3072
	v_lshl_add_u64 v[192:193], s[48:49], 0, v[136:137]
	s_add_i32 m0, s13, 0xc000
	ds_read_b128 v[176:179], v143
	ds_read_b128 v[180:183], v143 offset:1024
	ds_read_b128 v[184:187], v143 offset:2048
	ds_read_b128 v[188:191], v143 offset:3072
	ds_read_b128 v[198:201], v143 offset:4096
	ds_read_b128 v[202:205], v143 offset:5120
	ds_read_b128 v[206:209], v143 offset:6144
	ds_read_b128 v[210:213], v143 offset:7168
	global_load_lds_dwordx4 v[192:193], off
	v_lshl_add_u64 v[192:193], s[48:49], 0, v[138:139]
	s_add_i32 m0, s13, 0xe000
	s_nop 0
	global_load_lds_dwordx4 v[192:193], off
	s_waitcnt vmcnt(16)
	s_waitcnt lgkmcnt(0)
	s_barrier
	s_setprio 1
	s_waitcnt lgkmcnt(0)
	v_mfma_f32_16x16x32_bf16 v[126:129], v[144:147], v[176:179], 0
	v_mfma_f32_16x16x32_bf16 v[122:125], v[152:155], v[176:179], 0
	v_mfma_f32_16x16x32_bf16 v[118:121], v[144:147], v[184:187], 0
	v_mfma_f32_16x16x32_bf16 v[114:117], v[152:155], v[184:187], 0
	v_mfma_f32_16x16x32_bf16 v[102:105], v[144:147], v[198:201], 0
	v_mfma_f32_16x16x32_bf16 v[98:101], v[152:155], v[198:201], 0
	v_mfma_f32_16x16x32_bf16 v[86:89], v[144:147], v[206:209], 0
	v_mfma_f32_16x16x32_bf16 v[82:85], v[152:155], v[206:209], 0
	v_mfma_f32_16x16x32_bf16 v[126:129], v[148:151], v[180:183], v[126:129]
	v_mfma_f32_16x16x32_bf16 v[122:125], v[156:159], v[180:183], v[122:125]
	v_mfma_f32_16x16x32_bf16 v[118:121], v[148:151], v[188:191], v[118:121]
	v_mfma_f32_16x16x32_bf16 v[114:117], v[156:159], v[188:191], v[114:117]
	v_mfma_f32_16x16x32_bf16 v[102:105], v[148:151], v[202:205], v[102:105]
	v_mfma_f32_16x16x32_bf16 v[98:101], v[156:159], v[202:205], v[98:101]
	v_mfma_f32_16x16x32_bf16 v[86:89], v[148:151], v[210:213], v[86:89]
	v_mfma_f32_16x16x32_bf16 v[82:85], v[156:159], v[210:213], v[82:85]
	s_setprio 0
	s_setprio 1
	v_mfma_f32_16x16x32_bf16 v[110:113], v[160:163], v[176:179], 0
	v_mfma_f32_16x16x32_bf16 v[106:109], v[168:171], v[176:179], 0
	v_mfma_f32_16x16x32_bf16 v[94:97], v[160:163], v[184:187], 0
	v_mfma_f32_16x16x32_bf16 v[90:93], v[168:171], v[184:187], 0
	v_mfma_f32_16x16x32_bf16 v[78:81], v[160:163], v[198:201], 0
	v_mfma_f32_16x16x32_bf16 v[74:77], v[168:171], v[198:201], 0
	v_mfma_f32_16x16x32_bf16 v[70:73], v[160:163], v[206:209], 0
	v_mfma_f32_16x16x32_bf16 v[66:69], v[168:171], v[206:209], 0
	v_mfma_f32_16x16x32_bf16 v[110:113], v[164:167], v[180:183], v[110:113]
	v_mfma_f32_16x16x32_bf16 v[106:109], v[172:175], v[180:183], v[106:109]
	v_mfma_f32_16x16x32_bf16 v[94:97], v[164:167], v[188:191], v[94:97]
	v_mfma_f32_16x16x32_bf16 v[90:93], v[172:175], v[188:191], v[90:93]
	v_mfma_f32_16x16x32_bf16 v[78:81], v[164:167], v[202:205], v[78:81]
	v_mfma_f32_16x16x32_bf16 v[74:77], v[172:175], v[202:205], v[74:77]
	v_mfma_f32_16x16x32_bf16 v[70:73], v[164:167], v[210:213], v[70:73]
	v_mfma_f32_16x16x32_bf16 v[66:69], v[172:175], v[210:213], v[66:69]
	s_setprio 0
	s_barrier
	s_add_i32 s46, s47, s37
	v_lshl_add_u64 v[192:193], s[52:53], 0, v[32:33]
	s_mov_b32 m0, s46
	ds_read_b128 v[176:179], v143 offset:16384
	ds_read_b128 v[180:183], v143 offset:17408
	ds_read_b128 v[184:187], v143 offset:18432
	ds_read_b128 v[188:191], v143 offset:19456
	ds_read_b128 v[198:201], v143 offset:20480
	ds_read_b128 v[202:205], v143 offset:21504
	ds_read_b128 v[206:209], v143 offset:22528
	ds_read_b128 v[210:213], v143 offset:23552
	global_load_lds_dwordx4 v[192:193], off
	s_add_i32 m0, s46, 0x2000
	s_add_u32 s46, s52, 0x80000
	v_lshl_add_u64 v[214:215], s[52:53], 0, v[134:135]
	s_addc_u32 s47, s53, 0
	s_add_i32 s45, s45, s37
	global_load_lds_dwordx4 v[214:215], off
	v_lshl_add_u64 v[216:217], s[46:47], 0, v[32:33]
	s_mov_b32 m0, s45
	v_lshl_add_u64 v[218:219], s[56:57], 0, v[132:133]
	global_load_lds_dwordx4 v[216:217], off
	v_lshl_add_u64 v[216:217], s[46:47], 0, v[134:135]
	s_add_i32 m0, s45, 0x2000
	s_nop 0
	global_load_lds_dwordx4 v[216:217], off
	v_lshl_add_u64 v[216:217], s[56:57], 0, v[130:131]
	s_mov_b32 m0, s13
	s_nop 0
	global_load_lds_dwordx4 v[216:217], off
	s_mov_b32 m0, s24
	s_nop 0
	global_load_lds_dwordx4 v[218:219], off
	v_lshl_add_u32 v246, s68, 8, v140
	v_add_u32_e32 v246, 0x80, v246
	v_lshl_or_b32 v222, s69, 8, v142
	v_lshlrev_b32_e32 v222, 1, v222
	v_mov_b32_e32 v223, 0
	v_mad_u64_u32 v[248:249], s[70:71], v246, s67, v[222:223]
	s_mov_b32 s72, 0xa2000
	s_mov_b32 s73, 0
	v_lshl_add_u64 v[248:249], v[248:249], 0, s[76:77]
	v_cvt_pk_bf16_f32 v62, v62, v63
	v_cvt_pk_bf16_f32 v63, v64, v65
	v_cvt_pk_bf16_f32 v64, v58, v59
	v_cvt_pk_bf16_f32 v65, v60, v61
	global_store_dwordx4 v[248:249], v[62:65], off
	v_cvt_pk_bf16_f32 v46, v46, v47
	v_cvt_pk_bf16_f32 v47, v48, v49
	v_cvt_pk_bf16_f32 v48, v42, v43
	v_cvt_pk_bf16_f32 v49, v44, v45
	global_store_dwordx4 v[248:249], v[46:49], off offset:256
	v_lshl_add_u64 v[248:249], v[248:249], 0, s[72:73]
	v_cvt_pk_bf16_f32 v54, v54, v55
	v_cvt_pk_bf16_f32 v55, v56, v57
	v_cvt_pk_bf16_f32 v56, v50, v51
	v_cvt_pk_bf16_f32 v57, v52, v53
	global_store_dwordx4 v[248:249], v[54:57], off
	v_cvt_pk_bf16_f32 v28, v28, v29
	v_cvt_pk_bf16_f32 v29, v30, v31
	v_cvt_pk_bf16_f32 v30, v24, v25
	v_cvt_pk_bf16_f32 v31, v26, v27
	global_store_dwordx4 v[248:249], v[28:31], off offset:256
	v_lshl_add_u64 v[248:249], v[248:249], 0, s[72:73]
	v_cvt_pk_bf16_f32 v38, v38, v39
	v_cvt_pk_bf16_f32 v39, v40, v41
	v_cvt_pk_bf16_f32 v40, v34, v35
	v_cvt_pk_bf16_f32 v41, v36, v37
	global_store_dwordx4 v[248:249], v[38:41], off
	v_cvt_pk_bf16_f32 v12, v12, v13
	v_cvt_pk_bf16_f32 v13, v14, v15
	v_cvt_pk_bf16_f32 v14, v8, v9
	v_cvt_pk_bf16_f32 v15, v10, v11
	global_store_dwordx4 v[248:249], v[12:15], off offset:256
	v_lshl_add_u64 v[248:249], v[248:249], 0, s[72:73]
	v_cvt_pk_bf16_f32 v20, v20, v21
	v_cvt_pk_bf16_f32 v21, v22, v23
	v_cvt_pk_bf16_f32 v22, v16, v17
	v_cvt_pk_bf16_f32 v23, v18, v19
	global_store_dwordx4 v[248:249], v[20:23], off
	v_cvt_pk_bf16_f32 v4, v4, v5
	v_cvt_pk_bf16_f32 v5, v6, v7
	v_cvt_pk_bf16_f32 v6, v0, v1
	v_cvt_pk_bf16_f32 v7, v2, v3
	global_store_dwordx4 v[248:249], v[4:7], off offset:256
	s_waitcnt vmcnt(24)
	s_waitcnt lgkmcnt(0)
	s_barrier
; #define PG8_STAGE(bufoff, gbase, voff) do { _Pragma("unroll") for (int _i = 0; _i < 2; ++_i) \
;         __builtin_amdgcn_global_load_lds((const unsigned*)((const char*)(gbase) + (voff)[_i]), (PG8_LAS unsigned*)(lds + (bufoff) + ldsw + _i * 8192), 16, 0, 0); } while (0)
; #define PG8_LDA(dst, b, h) do { _Pragma("unroll") for (int m = 0; m < 4; ++m) _Pragma("unroll") for (int k = 0; k < 2; ++k) dst[m][k] = *(const PG8_LAS bf16x8*)(lds + PG8_SA(b, h) + aoff + m * 2048 + k * 1024); } while (0)
; #define PG8_LDB(dst, b, h) do { _Pragma("unroll") for (int n = 0; n < 2; ++n) _Pragma("unroll") for (int k = 0; k < 2; ++k) dst[n][k] = *(const PG8_LAS bf16x8*)(lds + PG8_SB(b, h) + boff + n * 2048 + k * 1024); } while (0)
; #define PG8_MMA(ai, bj, At, Bt) do { __builtin_amdgcn_s_setprio(1); _Pragma("unroll") for (int m = 0; m < 4; ++m) _Pragma("unroll") for (int n = 0; n < 2; ++n) _Pragma("unroll") for (int k = 0; k < 2; ++k) \
;         acc[ai][bj][m][n] = __builtin_amdgcn_mfma_f32_16x16x32_bf16(Bt[n][k], At[m][k], acc[ai][bj][m][n], 0, 0, 0); __builtin_amdgcn_s_setprio(0); } while (0)
; #define PG8_WAIT_V(n) asm volatile("s_waitcnt vmcnt(" #n ")" ::: "memory")
; #define PG8_WAIT_L(n) asm volatile("s_waitcnt lgkmcnt(" #n ")" ::: "memory")
; #define PG8_BAR __builtin_amdgcn_s_barrier()
; #define PG8_SCHED __builtin_amdgcn_sched_barrier(0)
; template <class Epi, class Sched, bool ALIGN_EPI = false, bool SP2 = false, bool KHOOK = false>
; __device__ __forceinline__ void gemm_phase(PG8_LAS unsigned char* lds, const Gemm g, const Sched& S, const Epi& E, const int tid_in) {
;     ...
;             PG8_WAIT_V(8); PG8_WAIT_L(0); PG8_BAR; PG8_MMA(1, 0, At, B0); PG8_MMA(1, 1, At, B1); PG8_BAR; PG8_SCHED;
;             PG8_LDB(B0, 1, 0); PG8_LDB(B1, 1, 1); PG8_SCHED; PG8_LDA(At, 1, 0); PG8_STAGE(PG8_SA(0, 1), a2 + hstep, voffA);
;             PG8_WAIT_V(8); PG8_WAIT_L(0); PG8_BAR; PG8_MMA(0, 0, At, B0); PG8_MMA(0, 1, At, B1); PG8_BAR; PG8_SCHED;
	s_setprio 1
	s_waitcnt lgkmcnt(0)
	v_mfma_f32_16x16x32_bf16 v[62:65], v[144:147], v[176:179], 0
	v_mfma_f32_16x16x32_bf16 v[58:61], v[152:155], v[176:179], 0
	v_mfma_f32_16x16x32_bf16 v[54:57], v[144:147], v[184:187], 0
	v_mfma_f32_16x16x32_bf16 v[50:53], v[152:155], v[184:187], 0
	v_mfma_f32_16x16x32_bf16 v[38:41], v[144:147], v[198:201], 0
	v_mfma_f32_16x16x32_bf16 v[34:37], v[152:155], v[198:201], 0
	v_mfma_f32_16x16x32_bf16 v[20:23], v[144:147], v[206:209], 0
	v_mfma_f32_16x16x32_bf16 v[16:19], v[152:155], v[206:209], 0
	v_mfma_f32_16x16x32_bf16 v[62:65], v[148:151], v[180:183], v[62:65]
	v_mfma_f32_16x16x32_bf16 v[58:61], v[156:159], v[180:183], v[58:61]
	v_mfma_f32_16x16x32_bf16 v[54:57], v[148:151], v[188:191], v[54:57]
	v_mfma_f32_16x16x32_bf16 v[50:53], v[156:159], v[188:191], v[50:53]
	v_mfma_f32_16x16x32_bf16 v[38:41], v[148:151], v[202:205], v[38:41]
	v_mfma_f32_16x16x32_bf16 v[34:37], v[156:159], v[202:205], v[34:37]
	v_mfma_f32_16x16x32_bf16 v[20:23], v[148:151], v[210:213], v[20:23]
	v_mfma_f32_16x16x32_bf16 v[16:19], v[156:159], v[210:213], v[16:19]
	s_setprio 0
	s_setprio 1
	v_mfma_f32_16x16x32_bf16 v[46:49], v[160:163], v[176:179], 0
	v_mfma_f32_16x16x32_bf16 v[42:45], v[168:171], v[176:179], 0
	v_mfma_f32_16x16x32_bf16 v[28:31], v[160:163], v[184:187], 0
	v_mfma_f32_16x16x32_bf16 v[24:27], v[168:171], v[184:187], 0
	v_mfma_f32_16x16x32_bf16 v[12:15], v[160:163], v[198:201], 0
	v_mfma_f32_16x16x32_bf16 v[8:11], v[168:171], v[198:201], 0
	v_mfma_f32_16x16x32_bf16 v[4:7], v[160:163], v[206:209], 0
	v_mfma_f32_16x16x32_bf16 v[0:3], v[168:171], v[206:209], 0
	v_mfma_f32_16x16x32_bf16 v[46:49], v[164:167], v[180:183], v[46:49]
	v_mfma_f32_16x16x32_bf16 v[42:45], v[172:175], v[180:183], v[42:45]
	v_mfma_f32_16x16x32_bf16 v[28:31], v[164:167], v[188:191], v[28:31]
	v_mfma_f32_16x16x32_bf16 v[24:27], v[172:175], v[188:191], v[24:27]
	v_mfma_f32_16x16x32_bf16 v[12:15], v[164:167], v[202:205], v[12:15]
	v_mfma_f32_16x16x32_bf16 v[8:11], v[172:175], v[202:205], v[8:11]
	v_mfma_f32_16x16x32_bf16 v[4:7], v[164:167], v[210:213], v[4:7]
	v_mfma_f32_16x16x32_bf16 v[0:3], v[172:175], v[210:213], v[0:3]
	s_setprio 0
	s_barrier
	s_add_i32 s45, 0, 0x18000
	s_add_i32 s50, 0, 0x1c000
	v_add_u32_e32 v156, s45, v141
	v_add_u32_e32 v172, s50, v141
	ds_read_b128 v[144:147], v156
	ds_read_b128 v[148:151], v156 offset:1024
	ds_read_b128 v[152:155], v156 offset:2048
	ds_read_b128 v[156:159], v156 offset:3072
	ds_read_b128 v[160:163], v172
	ds_read_b128 v[164:167], v172 offset:1024
	ds_read_b128 v[168:171], v172 offset:2048
	ds_read_b128 v[172:175], v172 offset:3072
	s_add_u32 s46, s56, 0x80000
	s_addc_u32 s47, s57, 0
	s_mov_b32 m0, s25
	v_lshl_add_u64 v[220:221], s[46:47], 0, v[130:131]
	ds_read_b128 v[176:179], v143 offset:32768
	ds_read_b128 v[180:183], v143 offset:33792
	ds_read_b128 v[184:187], v143 offset:34816
	ds_read_b128 v[188:191], v143 offset:35840
	ds_read_b128 v[198:201], v143 offset:36864
	ds_read_b128 v[202:205], v143 offset:37888
	ds_read_b128 v[206:209], v143 offset:38912
	ds_read_b128 v[210:213], v143 offset:39936
	global_load_lds_dwordx4 v[220:221], off
	v_lshl_add_u64 v[220:221], s[46:47], 0, v[132:133]
	s_mov_b32 m0, s38
	s_nop 0
	global_load_lds_dwordx4 v[220:221], off
	s_waitcnt vmcnt(16)
	s_waitcnt lgkmcnt(0)
	s_barrier
	s_setprio 1
	s_waitcnt lgkmcnt(0)
	v_mfma_f32_16x16x32_bf16 v[126:129], v[144:147], v[176:179], v[126:129]
	v_mfma_f32_16x16x32_bf16 v[122:125], v[152:155], v[176:179], v[122:125]
	v_mfma_f32_16x16x32_bf16 v[118:121], v[144:147], v[184:187], v[118:121]
	v_mfma_f32_16x16x32_bf16 v[114:117], v[152:155], v[184:187], v[114:117]
	v_mfma_f32_16x16x32_bf16 v[102:105], v[144:147], v[198:201], v[102:105]
	v_mfma_f32_16x16x32_bf16 v[98:101], v[152:155], v[198:201], v[98:101]
	v_mfma_f32_16x16x32_bf16 v[86:89], v[144:147], v[206:209], v[86:89]
	v_mfma_f32_16x16x32_bf16 v[82:85], v[152:155], v[206:209], v[82:85]
	v_mfma_f32_16x16x32_bf16 v[126:129], v[148:151], v[180:183], v[126:129]
	v_mfma_f32_16x16x32_bf16 v[122:125], v[156:159], v[180:183], v[122:125]
	v_mfma_f32_16x16x32_bf16 v[118:121], v[148:151], v[188:191], v[118:121]
	v_mfma_f32_16x16x32_bf16 v[114:117], v[156:159], v[188:191], v[114:117]
	v_mfma_f32_16x16x32_bf16 v[102:105], v[148:151], v[202:205], v[102:105]
	v_mfma_f32_16x16x32_bf16 v[98:101], v[156:159], v[202:205], v[98:101]
	v_mfma_f32_16x16x32_bf16 v[86:89], v[148:151], v[210:213], v[86:89]
	v_mfma_f32_16x16x32_bf16 v[82:85], v[156:159], v[210:213], v[82:85]
	s_setprio 0
	s_setprio 1
	v_mfma_f32_16x16x32_bf16 v[110:113], v[160:163], v[176:179], v[110:113]
	v_mfma_f32_16x16x32_bf16 v[106:109], v[168:171], v[176:179], v[106:109]
	v_mfma_f32_16x16x32_bf16 v[94:97], v[160:163], v[184:187], v[94:97]
	v_mfma_f32_16x16x32_bf16 v[90:93], v[168:171], v[184:187], v[90:93]
	v_mfma_f32_16x16x32_bf16 v[78:81], v[160:163], v[198:201], v[78:81]
	v_mfma_f32_16x16x32_bf16 v[74:77], v[168:171], v[198:201], v[74:77]
	v_mfma_f32_16x16x32_bf16 v[70:73], v[160:163], v[206:209], v[70:73]
	v_mfma_f32_16x16x32_bf16 v[66:69], v[168:171], v[206:209], v[66:69]
	v_mfma_f32_16x16x32_bf16 v[110:113], v[164:167], v[180:183], v[110:113]
	v_mfma_f32_16x16x32_bf16 v[106:109], v[172:175], v[180:183], v[106:109]
	v_mfma_f32_16x16x32_bf16 v[94:97], v[164:167], v[188:191], v[94:97]
	v_mfma_f32_16x16x32_bf16 v[90:93], v[172:175], v[188:191], v[90:93]
	v_mfma_f32_16x16x32_bf16 v[78:81], v[164:167], v[202:205], v[78:81]
	v_mfma_f32_16x16x32_bf16 v[74:77], v[172:175], v[202:205], v[74:77]
	v_mfma_f32_16x16x32_bf16 v[70:73], v[164:167], v[210:213], v[70:73]
	v_mfma_f32_16x16x32_bf16 v[66:69], v[172:175], v[210:213], v[66:69]
	s_setprio 0
	s_barrier
; #define PG8_STAGE(bufoff, gbase, voff) do { _Pragma("unroll") for (int _i = 0; _i < 2; ++_i) \
;         __builtin_amdgcn_global_load_lds((const unsigned*)((const char*)(gbase) + (voff)[_i]), (PG8_LAS unsigned*)(lds + (bufoff) + ldsw + _i * 8192), 16, 0, 0); } while (0)
; #define PG8_LDA(dst, b, h) do { _Pragma("unroll") for (int m = 0; m < 4; ++m) _Pragma("unroll") for (int k = 0; k < 2; ++k) dst[m][k] = *(const PG8_LAS bf16x8*)(lds + PG8_SA(b, h) + aoff + m * 2048 + k * 1024); } while (0)
; #define PG8_MMA(ai, bj, At, Bt) do { __builtin_amdgcn_s_setprio(1); _Pragma("unroll") for (int m = 0; m < 4; ++m) _Pragma("unroll") for (int n = 0; n < 2; ++n) _Pragma("unroll") for (int k = 0; k < 2; ++k) \
;         acc[ai][bj][m][n] = __builtin_amdgcn_mfma_f32_16x16x32_bf16(Bt[n][k], At[m][k], acc[ai][bj][m][n], 0, 0, 0); __builtin_amdgcn_s_setprio(0); } while (0)
; #define PG8_WAIT_V(n) asm volatile("s_waitcnt vmcnt(" #n ")" ::: "memory")
; #define PG8_WAIT_L(n) asm volatile("s_waitcnt lgkmcnt(" #n ")" ::: "memory")
; #define PG8_BAR __builtin_amdgcn_s_barrier()
; #define PG8_SCHED __builtin_amdgcn_sched_barrier(0)
; template <class Epi, class Sched, bool ALIGN_EPI = false, bool SP2 = false, bool KHOOK = false>
; __device__ __forceinline__ void gemm_phase(PG8_LAS unsigned char* lds, const Gemm g, const Sched& S, const Epi& E, const int tid_in) {
;     ...
;             PG8_LDA(At, 1, 1); PG8_STAGE(PG8_SB(1, 0), b3, voffB); PG8_STAGE(PG8_SB(1, 1), b3 + hstep, voffB); PG8_STAGE(PG8_SA(1, 0), a3, voffA);
;             PG8_WAIT_V(8); PG8_WAIT_L(0); PG8_BAR; PG8_MMA(1, 0, At, B0); PG8_MMA(1, 1, At, B1); PG8_BAR; PG8_SCHED;
	s_add_i32 s45, s45, s37
	v_lshl_add_u64 v[192:193], v[192:193], 0, s[90:91]
	s_mov_b32 m0, s45
	ds_read_b128 v[176:179], v143 offset:49152
	ds_read_b128 v[180:183], v143 offset:50176
	ds_read_b128 v[184:187], v143 offset:51200
	ds_read_b128 v[188:191], v143 offset:52224
	ds_read_b128 v[198:201], v143 offset:53248
	ds_read_b128 v[202:205], v143 offset:54272
	ds_read_b128 v[206:209], v143 offset:55296
	ds_read_b128 v[210:213], v143 offset:56320
	global_load_lds_dwordx4 v[192:193], off
	s_add_i32 m0, s45, 0x2000
	s_add_u32 s46, s52, 0x80080
	v_lshl_add_u64 v[192:193], v[214:215], 0, s[90:91]
	s_addc_u32 s47, s53, 0
	s_add_i32 s45, s50, s37
	global_load_lds_dwordx4 v[192:193], off
	v_lshl_add_u64 v[192:193], s[46:47], 0, v[32:33]
	s_mov_b32 m0, s45
	s_nop 0
	global_load_lds_dwordx4 v[192:193], off
	v_lshl_add_u64 v[192:193], s[46:47], 0, v[134:135]
	s_add_i32 m0, s45, 0x2000
	s_nop 0
	global_load_lds_dwordx4 v[192:193], off
	v_lshl_add_u64 v[192:193], v[216:217], 0, s[90:91]
	s_mov_b32 m0, s39
	s_nop 0
	global_load_lds_dwordx4 v[192:193], off
	v_lshl_add_u64 v[192:193], v[218:219], 0, s[90:91]
	s_mov_b32 m0, s40
	s_nop 0
	global_load_lds_dwordx4 v[192:193], off
	s_waitcnt vmcnt(16)
	s_waitcnt lgkmcnt(0)
	s_barrier
	s_setprio 1
	s_waitcnt lgkmcnt(0)
	v_mfma_f32_16x16x32_bf16 v[62:65], v[144:147], v[176:179], v[62:65]
	v_mfma_f32_16x16x32_bf16 v[58:61], v[152:155], v[176:179], v[58:61]
	v_mfma_f32_16x16x32_bf16 v[54:57], v[144:147], v[184:187], v[54:57]
	v_mfma_f32_16x16x32_bf16 v[50:53], v[152:155], v[184:187], v[50:53]
	v_mfma_f32_16x16x32_bf16 v[38:41], v[144:147], v[198:201], v[38:41]
	v_mfma_f32_16x16x32_bf16 v[34:37], v[152:155], v[198:201], v[34:37]
	v_mfma_f32_16x16x32_bf16 v[20:23], v[144:147], v[206:209], v[20:23]
	v_mfma_f32_16x16x32_bf16 v[16:19], v[152:155], v[206:209], v[16:19]
	v_mfma_f32_16x16x32_bf16 v[62:65], v[148:151], v[180:183], v[62:65]
	v_mfma_f32_16x16x32_bf16 v[58:61], v[156:159], v[180:183], v[58:61]
	v_mfma_f32_16x16x32_bf16 v[54:57], v[148:151], v[188:191], v[54:57]
	v_mfma_f32_16x16x32_bf16 v[50:53], v[156:159], v[188:191], v[50:53]
	v_mfma_f32_16x16x32_bf16 v[38:41], v[148:151], v[202:205], v[38:41]
	v_mfma_f32_16x16x32_bf16 v[34:37], v[156:159], v[202:205], v[34:37]
	v_mfma_f32_16x16x32_bf16 v[20:23], v[148:151], v[210:213], v[20:23]
	v_mfma_f32_16x16x32_bf16 v[16:19], v[156:159], v[210:213], v[16:19]
	s_setprio 0
	s_setprio 1
	v_mfma_f32_16x16x32_bf16 v[46:49], v[160:163], v[176:179], v[46:49]
	v_mfma_f32_16x16x32_bf16 v[42:45], v[168:171], v[176:179], v[42:45]
	v_mfma_f32_16x16x32_bf16 v[28:31], v[160:163], v[184:187], v[28:31]
	v_mfma_f32_16x16x32_bf16 v[24:27], v[168:171], v[184:187], v[24:27]
	v_mfma_f32_16x16x32_bf16 v[12:15], v[160:163], v[198:201], v[12:15]
	v_mfma_f32_16x16x32_bf16 v[8:11], v[168:171], v[198:201], v[8:11]
	v_mfma_f32_16x16x32_bf16 v[4:7], v[160:163], v[206:209], v[4:7]
	v_mfma_f32_16x16x32_bf16 v[0:3], v[168:171], v[206:209], v[0:3]
	v_mfma_f32_16x16x32_bf16 v[46:49], v[164:167], v[180:183], v[46:49]
	v_mfma_f32_16x16x32_bf16 v[42:45], v[172:175], v[180:183], v[42:45]
	v_mfma_f32_16x16x32_bf16 v[28:31], v[164:167], v[188:191], v[28:31]
	v_mfma_f32_16x16x32_bf16 v[24:27], v[172:175], v[188:191], v[24:27]
	v_mfma_f32_16x16x32_bf16 v[12:15], v[164:167], v[202:205], v[12:15]
	v_mfma_f32_16x16x32_bf16 v[8:11], v[172:175], v[202:205], v[8:11]
	v_mfma_f32_16x16x32_bf16 v[4:7], v[164:167], v[210:213], v[4:7]
	v_mfma_f32_16x16x32_bf16 v[0:3], v[172:175], v[210:213], v[0:3]
	s_setprio 0
	s_barrier
	s_add_i32 s44, s44, 2
	s_add_u32 s48, s48, 0x100
	s_addc_u32 s49, s49, 0
	s_add_u32 s19, s19, 0x100
	s_addc_u32 s42, s42, 0
	s_cmp_gt_u32 s44, 29
